# grid barrier: XCD leaders no longer add to the (now unread) per-XCD release word, one atomic round trip less on the last arriver's path
# baseline (speedup 1.0000x reference)
.LBB0_97:
	s_or_b64 exec, exec, s[6:7]
	s_mov_b64 s[6:7], exec
	v_mbcnt_lo_u32_b32 v0, s6, 0
	v_mbcnt_hi_u32_b32 v0, s7, v0
	v_cmp_eq_u32_e32 vcc, 0, v0
	s_waitcnt vmcnt(0)
	buffer_inv sc1
	s_and_saveexec_b64 s[8:9], vcc
	s_cbranch_execz .LBB0_99
	s_bcnt1_i32_b64 s6, s[6:7]
	v_mov_b32_e32 v0, 0x2000
	v_mov_b32_e32 v1, s6
.LBB0_99:
	s_or_b64 exec, exec, s[8:9]
	s_waitcnt vmcnt(0)

.LBB0_212:
	s_or_b64 exec, exec, s[8:9]
	s_mov_b64 s[0:1], exec
	v_mbcnt_lo_u32_b32 v0, s0, 0
	v_mbcnt_hi_u32_b32 v0, s1, v0
	v_cmp_eq_u32_e32 vcc, 0, v0
	s_waitcnt vmcnt(0)
	buffer_inv sc1
	s_and_saveexec_b64 s[8:9], vcc
	s_cbranch_execz .LBB0_214
	s_bcnt1_i32_b64 s0, s[0:1]
	v_mov_b32_e32 v0, s0
.LBB0_214:
	s_or_b64 exec, exec, s[8:9]
	s_waitcnt vmcnt(0)

.LBB0_676:
	s_or_b64 exec, exec, s[8:9]
	s_mov_b64 s[0:1], exec
	v_mbcnt_lo_u32_b32 v0, s0, 0
	v_mbcnt_hi_u32_b32 v0, s1, v0
	v_cmp_eq_u32_e32 vcc, 0, v0
	s_waitcnt vmcnt(0)
	buffer_inv sc1
	s_and_saveexec_b64 s[8:9], vcc
	s_cbranch_execz .LBB0_678
	s_bcnt1_i32_b64 s0, s[0:1]
	v_mov_b32_e32 v0, s0
.LBB0_678:
	s_or_b64 exec, exec, s[8:9]
	s_waitcnt vmcnt(0)

.LBB0_756:
	s_or_b64 exec, exec, s[8:9]
	s_mov_b64 s[0:1], exec
	v_mbcnt_lo_u32_b32 v0, s0, 0
	v_mbcnt_hi_u32_b32 v0, s1, v0
	v_cmp_eq_u32_e32 vcc, 0, v0
	s_waitcnt vmcnt(0)
	buffer_inv sc1
	s_and_saveexec_b64 s[8:9], vcc
	s_cbranch_execz .LBB0_758
	s_bcnt1_i32_b64 s0, s[0:1]
	v_mov_b32_e32 v0, s0
.LBB0_758:
	s_or_b64 exec, exec, s[8:9]
	s_waitcnt vmcnt(0)

.LBB0_828:
	s_or_b64 exec, exec, s[8:9]
	s_mov_b64 s[0:1], exec
	v_mbcnt_lo_u32_b32 v0, s0, 0
	v_mbcnt_hi_u32_b32 v0, s1, v0
	v_cmp_eq_u32_e32 vcc, 0, v0
	s_waitcnt vmcnt(0)
	buffer_inv sc1
	s_and_saveexec_b64 s[8:9], vcc
	s_cbranch_execz .LBB0_830
	s_bcnt1_i32_b64 s0, s[0:1]
	v_mov_b32_e32 v0, s0
.LBB0_830:
	s_or_b64 exec, exec, s[8:9]
	s_waitcnt vmcnt(0)

.LBB0_890:
	s_or_b64 exec, exec, s[8:9]
	s_mov_b64 s[0:1], exec
	v_mbcnt_lo_u32_b32 v0, s0, 0
	v_mbcnt_hi_u32_b32 v0, s1, v0
	v_cmp_eq_u32_e32 vcc, 0, v0
	s_waitcnt vmcnt(0)
	buffer_inv sc1
	s_and_saveexec_b64 s[8:9], vcc
	s_cbranch_execz .LBB0_128
	s_bcnt1_i32_b64 s0, s[0:1]
	v_mov_b32_e32 v0, s0
	s_branch .LBB0_128
